# sparse attention QK: relative-position bias bucket computed once per query (all lanes) into dead LDS score slots instead of per tile epilogue
# speedup vs baseline: 1.0164x; 1.0003x over previous
; #define LAS __attribute__((address_space(3)))
; __device__ __forceinline__ void dsa_unit(int wv, const Args& A, LAS unsigned char* lds, int s, int qt) {
;     ...
;     for (int qi2 = 0; qi2 < 2; ++qi2) {
;         const int qq = 2 * w + qi2; int n = __builtin_amdgcn_readfirstlane((int)cnt[qq]); n = n > 256 ? 256 : n;
;         const size_t qrow = qrow0 + qq; const int qpos = qpos0 + qq;
;         LAS const unsigned short* lst = ci + qq * CAP;
;         long qf[8];
; #pragma unroll
;         for (int kk = 0; kk < 8; ++kk) { qf[kk] = 0;
;             if (fr < 8 && (fr >> 2) == (kk >> 2)) { const h16x8 q = __builtin_bit_cast(h16x8, *(const u32x4*)(PROJ + qrow * PW + C_Q + fr * 128 + ((kk >> 1) & 1) * 64 + fq * 16 + (kk & 1) * 8));
;                 f32x4 a, bq;
; #pragma unroll
;                 for (int e = 0; e < 4; ++e) { a[e] = 16.f * (float)q[e]; bq[e] = 16.f * (float)q[4 + e]; }
;                 qf[kk] = __builtin_bit_cast(long, pack_fp8x8(a, bq)); } }
;         const int nt = n >> 4;
;         long kf[8];
;     ...
;         DSA_LOADT(kf, 0);
.LBB0_1429:
	s_or_b32 s1, s0, s94
	s_lshl_b32 s12, s1, 2
	s_add_i32 s12, s12, 0
	s_add_i32 s12, s12, 0x1c800
	v_mov_b32_e32 v0, s12
	ds_read_b32 v0, v0
	s_ashr_i32 s12, s1, 31
	s_add_u32 s22, s1, s5
	s_addc_u32 s23, s12, 0
	s_mul_i32 s14, s23, 0x2e00
	v_mad_u64_u32 v[2:3], s[12:13], s22, v157, v[22:23]
	s_waitcnt lgkmcnt(0)
	v_readfirstlane_b32 s30, v0
	v_add_u32_e32 v3, s14, v3
	v_mov_b64_e32 v[32:33], 0
	v_mov_b64_e32 v[34:35], 0
	v_mov_b64_e32 v[36:37], 0
	v_mov_b64_e32 v[38:39], 0
	v_mov_b64_e32 v[40:41], 0
	v_mov_b64_e32 v[42:43], 0
	v_mov_b64_e32 v[44:45], 0
	v_mov_b64_e32 v[46:47], 0
	s_or_b64 s[14:15], s[10:11], s[20:21]
	s_and_saveexec_b64 s[12:13], s[14:15]
	global_load_dwordx4 v[56:59], v[2:3], off
	global_load_dwordx4 v[60:63], v[2:3], off offset:16
	global_load_dwordx4 v[64:67], v[2:3], off offset:128
	global_load_dwordx4 v[68:71], v[2:3], off offset:144
	s_waitcnt vmcnt(3)
	v_cvt_f32_f16_e32 v145, v56
	v_cvt_f32_f16_e32 v146, v58
	v_cvt_f32_f16_sdwa v147, v56 dst_sel:DWORD dst_unused:UNUSED_PAD src0_sel:WORD_1
	v_cvt_f32_f16_sdwa v148, v58 dst_sel:DWORD dst_unused:UNUSED_PAD src0_sel:WORD_1
	v_mul_f32_e32 v145, 0x41800000, v145
	v_mul_f32_e32 v146, 0x41800000, v146
	v_mul_f32_e32 v147, 0x41800000, v147
	v_mul_f32_e32 v148, 0x41800000, v148
	v_cvt_f32_f16_e32 v149, v57
	v_cvt_f32_f16_e32 v158, v59
	v_cvt_f32_f16_sdwa v159, v57 dst_sel:DWORD dst_unused:UNUSED_PAD src0_sel:WORD_1
	v_cvt_f32_f16_sdwa v160, v59 dst_sel:DWORD dst_unused:UNUSED_PAD src0_sel:WORD_1
	v_cvt_pk_fp8_f32 v72, v145, v147
	v_cvt_pk_fp8_f32 v73, v146, v148
	v_mul_f32_e32 v149, 0x41800000, v149
	v_mul_f32_e32 v158, 0x41800000, v158
	v_mul_f32_e32 v159, 0x41800000, v159
	v_mul_f32_e32 v160, 0x41800000, v160
	v_cvt_pk_fp8_f32 v72, v149, v159 op_sel:[0,0,1]
	v_cvt_pk_fp8_f32 v73, v158, v160 op_sel:[0,0,1]
	s_waitcnt vmcnt(2)
	v_cvt_f32_f16_e32 v145, v60
	v_cvt_f32_f16_e32 v146, v62
	v_cvt_f32_f16_sdwa v147, v60 dst_sel:DWORD dst_unused:UNUSED_PAD src0_sel:WORD_1
	v_cvt_f32_f16_sdwa v148, v62 dst_sel:DWORD dst_unused:UNUSED_PAD src0_sel:WORD_1
	v_mul_f32_e32 v145, 0x41800000, v145
	v_mul_f32_e32 v146, 0x41800000, v146
	v_mul_f32_e32 v147, 0x41800000, v147
	v_mul_f32_e32 v148, 0x41800000, v148
	v_cvt_f32_f16_e32 v149, v61
	v_cvt_f32_f16_e32 v158, v63
	v_cvt_f32_f16_sdwa v159, v61 dst_sel:DWORD dst_unused:UNUSED_PAD src0_sel:WORD_1
	v_cvt_f32_f16_sdwa v160, v63 dst_sel:DWORD dst_unused:UNUSED_PAD src0_sel:WORD_1
	v_cvt_pk_fp8_f32 v74, v145, v147
	v_cvt_pk_fp8_f32 v75, v146, v148
	v_mul_f32_e32 v149, 0x41800000, v149
	v_mul_f32_e32 v158, 0x41800000, v158
	v_mul_f32_e32 v159, 0x41800000, v159
	v_mul_f32_e32 v160, 0x41800000, v160
	v_cvt_pk_fp8_f32 v74, v149, v159 op_sel:[0,0,1]
	v_cvt_pk_fp8_f32 v75, v158, v160 op_sel:[0,0,1]
	s_waitcnt vmcnt(1)
	v_cvt_f32_f16_e32 v145, v64
	v_cvt_f32_f16_e32 v146, v66
	v_cvt_f32_f16_sdwa v147, v64 dst_sel:DWORD dst_unused:UNUSED_PAD src0_sel:WORD_1
	v_cvt_f32_f16_sdwa v148, v66 dst_sel:DWORD dst_unused:UNUSED_PAD src0_sel:WORD_1
	v_mul_f32_e32 v145, 0x41800000, v145
	v_mul_f32_e32 v146, 0x41800000, v146
	v_mul_f32_e32 v147, 0x41800000, v147
	v_mul_f32_e32 v148, 0x41800000, v148
	v_cvt_f32_f16_e32 v149, v65
	v_cvt_f32_f16_e32 v158, v67
	v_cvt_f32_f16_sdwa v159, v65 dst_sel:DWORD dst_unused:UNUSED_PAD src0_sel:WORD_1
	v_cvt_f32_f16_sdwa v160, v67 dst_sel:DWORD dst_unused:UNUSED_PAD src0_sel:WORD_1
	v_cvt_pk_fp8_f32 v76, v145, v147
	v_cvt_pk_fp8_f32 v77, v146, v148
	v_mul_f32_e32 v149, 0x41800000, v149
	v_mul_f32_e32 v158, 0x41800000, v158
	v_mul_f32_e32 v159, 0x41800000, v159
	v_mul_f32_e32 v160, 0x41800000, v160
	v_cvt_pk_fp8_f32 v76, v149, v159 op_sel:[0,0,1]
	v_cvt_pk_fp8_f32 v77, v158, v160 op_sel:[0,0,1]
	s_waitcnt vmcnt(0)
	v_cvt_f32_f16_e32 v145, v68
	v_cvt_f32_f16_e32 v146, v70
	v_cvt_f32_f16_sdwa v147, v68 dst_sel:DWORD dst_unused:UNUSED_PAD src0_sel:WORD_1
	v_cvt_f32_f16_sdwa v148, v70 dst_sel:DWORD dst_unused:UNUSED_PAD src0_sel:WORD_1
	v_mul_f32_e32 v145, 0x41800000, v145
	v_mul_f32_e32 v146, 0x41800000, v146
	v_mul_f32_e32 v147, 0x41800000, v147
	v_mul_f32_e32 v148, 0x41800000, v148
	v_cvt_f32_f16_e32 v149, v69
	v_cvt_f32_f16_e32 v158, v71
	v_cvt_f32_f16_sdwa v159, v69 dst_sel:DWORD dst_unused:UNUSED_PAD src0_sel:WORD_1
	v_cvt_f32_f16_sdwa v160, v71 dst_sel:DWORD dst_unused:UNUSED_PAD src0_sel:WORD_1
	v_cvt_pk_fp8_f32 v78, v145, v147
	v_cvt_pk_fp8_f32 v79, v146, v148
	v_mul_f32_e32 v149, 0x41800000, v149
	v_mul_f32_e32 v158, 0x41800000, v158
	v_mul_f32_e32 v159, 0x41800000, v159
	v_mul_f32_e32 v160, 0x41800000, v160
	v_cvt_pk_fp8_f32 v78, v149, v159 op_sel:[0,0,1]
	v_cvt_pk_fp8_f32 v79, v158, v160 op_sel:[0,0,1]
	s_nop 0
	v_cndmask_b32_e64 v34, 0, v72, s[10:11]
	v_cndmask_b32_e64 v35, 0, v73, s[10:11]
	v_cndmask_b32_e64 v42, 0, v72, s[20:21]
	v_cndmask_b32_e64 v43, 0, v73, s[20:21]
	v_cndmask_b32_e64 v32, 0, v74, s[10:11]
	v_cndmask_b32_e64 v33, 0, v75, s[10:11]
	v_cndmask_b32_e64 v40, 0, v74, s[20:21]
	v_cndmask_b32_e64 v41, 0, v75, s[20:21]
	v_cndmask_b32_e64 v38, 0, v76, s[10:11]
	v_cndmask_b32_e64 v39, 0, v77, s[10:11]
	v_cndmask_b32_e64 v46, 0, v76, s[20:21]
	v_cndmask_b32_e64 v47, 0, v77, s[20:21]
	v_cndmask_b32_e64 v36, 0, v78, s[10:11]
	v_cndmask_b32_e64 v37, 0, v79, s[10:11]
	v_cndmask_b32_e64 v44, 0, v78, s[20:21]
	v_cndmask_b32_e64 v45, 0, v79, s[20:21]
	s_or_b64 exec, exec, s[12:13]
	s_min_i32 s29, s30, 0x100
	s_ashr_i32 s16, s29, 4
	s_cmp_lt_i32 s16, 1
	s_mulk_i32 s0, 0x980
	s_cbranch_scc1 .LBB0_1458
; __device__ __forceinline__ void dsa_unit(int wv, const Args& A, LAS unsigned char* lds, int s, int qt) {
;     ...
;         DSA_LOADT(kf, 0);
;         for (int kt = 0; kt < nt; ++kt) {
;             long k1[8];
;             DSA_LOADT(k1, kt + 1);
;             f32x4 a = {0.f, 0.f, 0.f, 0.f};
; #pragma unroll
;             for (int kk = 0; kk < 8; ++kk) a = __builtin_amdgcn_mfma_f32_16x16x32_fp8_fp8(kf[kk], qf[kk], a, 0, 0, 0);
;             if (fr < 8) {
; #pragma unroll
;                 for (int r = 0; r < 4; ++r) { const int e2 = kt * 16 + fq * 4 + r; const int key2 = lst[e2];
;                     Pw[e2 * 8 + fr] = (h16)(a[r] * 0.0625f + relb[rel_bucket(key2 - qpos) * 8 + fr]); } }
	s_mul_i32 s12, s1, 0x980
	s_add_i32 s1, s1, s4
	v_lshl_add_u32 v141, v94, 1, s12
	v_add_u32_e32 v141, 0x13000, v141
	ds_read_u16 v107, v141
	ds_read_u16 v108, v141 offset:32
	ds_read_u16 v109, v141 offset:64
	ds_read_u16 v110, v141 offset:96
	ds_read_u16 v111, v141 offset:128
	ds_read_u16 v112, v141 offset:160
	ds_read_u16 v113, v141 offset:192
	ds_read_u16 v114, v141 offset:224
	ds_read_u16 v115, v141 offset:256
	ds_read_u16 v116, v141 offset:288
	ds_read_u16 v117, v141 offset:320
	ds_read_u16 v118, v141 offset:352
	ds_read_u16 v119, v141 offset:384
	ds_read_u16 v120, v141 offset:416
	ds_read_u16 v121, v141 offset:448
	ds_read_u16 v122, v141 offset:480
	v_mbcnt_lo_u32_b32 v144, -1, 0
	v_mbcnt_hi_u32_b32 v144, -1, v144
	v_lshl_add_u32 v30, v144, 3, s12
	v_add_u32_e32 v30, 0x13000, v30
	ds_read_b64 v[92:93], v30
	s_lshl_b32 s12, s12, 1
	v_lshl_add_u32 v28, v144, 4, s12
	v_add_u32_e32 v143, 0x1cc80, v103
	v_lshrrev_b32_e32 v144, 4, v144
	v_lshlrev_b32_e32 v144, 4, v144
	v_add_u32_e32 v29, s12, v144
	s_waitcnt lgkmcnt(0)
	v_add_lshl_u32 v107, s48, v107, 8
	v_add_u32_e32 v107, v144, v107
	global_load_dwordx4 v[56:59], v107, s[84:85]
	global_load_dwordx4 v[60:63], v107, s[84:85] offset:64
	global_load_dwordx4 v[64:67], v107, s[84:85] offset:128
	global_load_dwordx4 v[68:71], v107, s[84:85] offset:192
	s_cmp_gt_i32 s16, 1
	s_cbranch_scc0 .Lqk_ni_pre
	v_add_lshl_u32 v108, s48, v108, 8
	v_add_u32_e32 v108, v144, v108
	global_load_dwordx4 v[72:75], v108, s[84:85]
	global_load_dwordx4 v[76:79], v108, s[84:85] offset:64
	global_load_dwordx4 v[80:83], v108, s[84:85] offset:128
	global_load_dwordx4 v[84:87], v108, s[84:85] offset:192
.Lqk_ni_pre:
	v_and_b32_e32 v145, 0xffff, v92
	v_lshrrev_b32_e32 v146, 16, v92
	v_and_b32_e32 v147, 0xffff, v93
	v_lshrrev_b32_e32 v148, 16, v93
	v_subrev_u32_e32 v145, s1, v145
	v_subrev_u32_e32 v146, s1, v146
	v_subrev_u32_e32 v147, s1, v147
	v_subrev_u32_e32 v148, s1, v148
	v_sub_u32_e32 v149, 0, v145
	v_sub_u32_e32 v158, 0, v146
	v_sub_u32_e32 v159, 0, v147
	v_sub_u32_e32 v160, 0, v148
	v_max_i32_e32 v149, v145, v149
	v_max_i32_e32 v158, v146, v158
	v_max_i32_e32 v159, v147, v159
	v_max_i32_e32 v160, v148, v160
	v_mul_u32_u24_e32 v161, v149, v149
	v_mul_u32_u24_e32 v162, v158, v158
	v_mul_u32_u24_e32 v163, v159, v159
	v_mul_u32_u24_e32 v164, v160, v160
	v_cvt_f32_u32_e32 v161, v161
	v_cvt_f32_u32_e32 v162, v162
	v_cvt_f32_u32_e32 v163, v163
	v_cvt_f32_u32_e32 v164, v164
	v_lshrrev_b32_e32 v161, 23, v161
	v_lshrrev_b32_e32 v162, 23, v162
	v_lshrrev_b32_e32 v163, 23, v163
	v_lshrrev_b32_e32 v164, 23, v164
	v_add_u32_e32 v161, 0xffffff83, v161
	v_add_u32_e32 v162, 0xffffff83, v162
	v_add_u32_e32 v163, 0xffffff83, v163
	v_add_u32_e32 v164, 0xffffff83, v164
	v_min_u32_e32 v161, 15, v161
	v_min_u32_e32 v162, 15, v162
	v_min_u32_e32 v163, 15, v163
	v_min_u32_e32 v164, 15, v164
	v_cmp_gt_u32_e32 vcc, 8, v149
	v_cmp_gt_u32_e64 s[26:27], 8, v158
	v_cmp_gt_u32_e64 s[36:37], 8, v159
	v_cmp_gt_u32_e64 s[38:39], 8, v160
	v_med3_i32 v165, v145, 0, 1
	v_med3_i32 v166, v146, 0, 1
	v_med3_i32 v167, v147, 0, 1
	v_med3_i32 v168, v148, 0, 1
	v_cndmask_b32_e64 v161, v161, v149, vcc
	v_cndmask_b32_e64 v162, v162, v158, s[26:27]
	v_cndmask_b32_e64 v163, v163, v159, s[36:37]
	v_cndmask_b32_e64 v164, v164, v160, s[38:39]
	v_lshl_add_u32 v161, v165, 4, v161
	v_lshl_add_u32 v162, v166, 4, v162
	v_lshl_add_u32 v163, v167, 4, v163
	v_lshl_add_u32 v164, v168, 4, v164
	v_lshlrev_b32_e32 v48, 5, v161
	v_lshlrev_b32_e32 v49, 5, v162
	v_lshlrev_b32_e32 v50, 5, v163
	v_lshlrev_b32_e32 v51, 5, v164
	ds_write_b128 v28, v[48:51]
	ds_read_b128 v[52:55], v29
	s_cmp_gt_i32 s16, 2
	s_cbranch_scc0 .Lqk_ni_0
	v_add_lshl_u32 v109, s48, v109, 8
	v_add_u32_e32 v109, v144, v109
	global_load_dwordx4 v[124:127], v109, s[84:85]
	global_load_dwordx4 v[128:131], v109, s[84:85] offset:64
	global_load_dwordx4 v[132:135], v109, s[84:85] offset:128
	global_load_dwordx4 v[136:139], v109, s[84:85] offset:192
	s_waitcnt vmcnt(8)
	s_branch .Lqk_go_0

; __device__ __forceinline__ void dsa_unit(int wv, const Args& A, LAS unsigned char* lds, int s, int qt) {
;     ...
;         for (int kt = 0; kt < nt; ++kt) {
;             long k1[8];
;             DSA_LOADT(k1, kt + 1);
;             f32x4 a = {0.f, 0.f, 0.f, 0.f};
; #pragma unroll
;             for (int kk = 0; kk < 8; ++kk) a = __builtin_amdgcn_mfma_f32_16x16x32_fp8_fp8(kf[kk], qf[kk], a, 0, 0, 0);
;             if (fr < 8) {
; #pragma unroll
;                 for (int r = 0; r < 4; ++r) { const int e2 = kt * 16 + fq * 4 + r; const int key2 = lst[e2];
;                     Pw[e2 * 8 + fr] = (h16)(a[r] * 0.0625f + relb[rel_bucket(key2 - qpos) * 8 + fr]); } }
; #pragma unroll
;             for (int kk = 0; kk < 8; ++kk) kf[kk] = k1[kk];
.Lqk_go_0:
	v_mfma_f32_16x16x32_fp8_fp8 v[88:91], v[56:57], v[34:35], 0
	v_mfma_f32_16x16x32_fp8_fp8 v[88:91], v[58:59], v[32:33], v[88:91]
	v_mfma_f32_16x16x32_fp8_fp8 v[88:91], v[60:61], v[38:39], v[88:91]
	v_mfma_f32_16x16x32_fp8_fp8 v[88:91], v[62:63], v[36:37], v[88:91]
	v_mfma_f32_16x16x32_fp8_fp8 v[88:91], v[64:65], v[42:43], v[88:91]
	v_mfma_f32_16x16x32_fp8_fp8 v[88:91], v[66:67], v[40:41], v[88:91]
	v_mfma_f32_16x16x32_fp8_fp8 v[88:91], v[68:69], v[46:47], v[88:91]
	v_mfma_f32_16x16x32_fp8_fp8 v[88:91], v[70:71], v[44:45], v[88:91]
	s_and_saveexec_b64 s[12:13], s[8:9]
	s_waitcnt lgkmcnt(0)
	v_add_u32_e32 v165, v52, v25
	v_add_u32_e32 v166, v53, v25
	v_add_u32_e32 v167, v54, v25
	v_add_u32_e32 v168, v55, v25
	ds_read_b32 v165, v165
	ds_read_b32 v166, v166
	ds_read_b32 v167, v167
	ds_read_b32 v168, v168
	s_waitcnt lgkmcnt(3)
	v_fma_mixlo_f16 v165, v88, s3, v165
	s_waitcnt lgkmcnt(2)
	v_fma_mixlo_f16 v166, v89, s3, v166
	s_waitcnt lgkmcnt(1)
	v_fma_mixlo_f16 v167, v90, s3, v167
	s_waitcnt lgkmcnt(0)
	v_fma_mixlo_f16 v168, v91, s3, v168
	ds_write_b16 v143, v165
	ds_write_b16 v143, v166 offset:16
	ds_write_b16 v143, v167 offset:32
	ds_write_b16 v143, v168 offset:48
	s_mov_b64 exec, s[12:13]
	s_cmp_le_i32 s16, 1
	s_cbranch_scc1 .Lqk_done
	ds_read_b128 v[52:55], v29 offset:64
	s_cmp_gt_i32 s16, 3
	s_cbranch_scc0 .Lqk_ni_1
	v_add_lshl_u32 v110, s48, v110, 8
	v_add_u32_e32 v110, v144, v110
	global_load_dwordx4 v[56:59], v110, s[84:85]
	global_load_dwordx4 v[60:63], v110, s[84:85] offset:64
	global_load_dwordx4 v[64:67], v110, s[84:85] offset:128
	global_load_dwordx4 v[68:71], v110, s[84:85] offset:192
	s_waitcnt vmcnt(8)
	s_branch .Lqk_go_1

; __device__ __forceinline__ void dsa_unit(int wv, const Args& A, LAS unsigned char* lds, int s, int qt) {
;     ...
;         for (int kt = 0; kt < nt; ++kt) {
;             long k1[8];
;             DSA_LOADT(k1, kt + 1);
;             f32x4 a = {0.f, 0.f, 0.f, 0.f};
; #pragma unroll
;             for (int kk = 0; kk < 8; ++kk) a = __builtin_amdgcn_mfma_f32_16x16x32_fp8_fp8(kf[kk], qf[kk], a, 0, 0, 0);
;             if (fr < 8) {
; #pragma unroll
;                 for (int r = 0; r < 4; ++r) { const int e2 = kt * 16 + fq * 4 + r; const int key2 = lst[e2];
;                     Pw[e2 * 8 + fr] = (h16)(a[r] * 0.0625f + relb[rel_bucket(key2 - qpos) * 8 + fr]); } }
; #pragma unroll
;             for (int kk = 0; kk < 8; ++kk) kf[kk] = k1[kk];
.Lqk_go_1:
	v_mfma_f32_16x16x32_fp8_fp8 v[88:91], v[72:73], v[34:35], 0
	v_mfma_f32_16x16x32_fp8_fp8 v[88:91], v[74:75], v[32:33], v[88:91]
	v_mfma_f32_16x16x32_fp8_fp8 v[88:91], v[76:77], v[38:39], v[88:91]
	v_mfma_f32_16x16x32_fp8_fp8 v[88:91], v[78:79], v[36:37], v[88:91]
	v_mfma_f32_16x16x32_fp8_fp8 v[88:91], v[80:81], v[42:43], v[88:91]
	v_mfma_f32_16x16x32_fp8_fp8 v[88:91], v[82:83], v[40:41], v[88:91]
	v_mfma_f32_16x16x32_fp8_fp8 v[88:91], v[84:85], v[46:47], v[88:91]
	v_mfma_f32_16x16x32_fp8_fp8 v[88:91], v[86:87], v[44:45], v[88:91]
	s_and_saveexec_b64 s[12:13], s[8:9]
	s_waitcnt lgkmcnt(0)
	v_add_u32_e32 v165, v52, v25
	v_add_u32_e32 v166, v53, v25
	v_add_u32_e32 v167, v54, v25
	v_add_u32_e32 v168, v55, v25
	ds_read_b32 v165, v165
	ds_read_b32 v166, v166
	ds_read_b32 v167, v167
	ds_read_b32 v168, v168
	s_waitcnt lgkmcnt(3)
	v_fma_mixlo_f16 v165, v88, s3, v165
	s_waitcnt lgkmcnt(2)
	v_fma_mixlo_f16 v166, v89, s3, v166
	s_waitcnt lgkmcnt(1)
	v_fma_mixlo_f16 v167, v90, s3, v167
	s_waitcnt lgkmcnt(0)
	v_fma_mixlo_f16 v168, v91, s3, v168
	ds_write_b16 v143, v165 offset:256
	ds_write_b16 v143, v166 offset:272
	ds_write_b16 v143, v167 offset:288
	ds_write_b16 v143, v168 offset:304
	s_mov_b64 exec, s[12:13]
	s_cmp_le_i32 s16, 2
	s_cbranch_scc1 .Lqk_done
	ds_read_b128 v[52:55], v29 offset:128
	s_cmp_gt_i32 s16, 4
	s_cbranch_scc0 .Lqk_ni_2
	v_add_lshl_u32 v111, s48, v111, 8
	v_add_u32_e32 v111, v144, v111
	global_load_dwordx4 v[72:75], v111, s[84:85]
	global_load_dwordx4 v[76:79], v111, s[84:85] offset:64
	global_load_dwordx4 v[80:83], v111, s[84:85] offset:128
	global_load_dwordx4 v[84:87], v111, s[84:85] offset:192
	s_waitcnt vmcnt(8)
	s_branch .Lqk_go_2

; __device__ __forceinline__ void dsa_unit(int wv, const Args& A, LAS unsigned char* lds, int s, int qt) {
;     ...
;         for (int kt = 0; kt < nt; ++kt) {
;             long k1[8];
;             DSA_LOADT(k1, kt + 1);
;             f32x4 a = {0.f, 0.f, 0.f, 0.f};
; #pragma unroll
;             for (int kk = 0; kk < 8; ++kk) a = __builtin_amdgcn_mfma_f32_16x16x32_fp8_fp8(kf[kk], qf[kk], a, 0, 0, 0);
;             if (fr < 8) {
; #pragma unroll
;                 for (int r = 0; r < 4; ++r) { const int e2 = kt * 16 + fq * 4 + r; const int key2 = lst[e2];
;                     Pw[e2 * 8 + fr] = (h16)(a[r] * 0.0625f + relb[rel_bucket(key2 - qpos) * 8 + fr]); } }
; #pragma unroll
;             for (int kk = 0; kk < 8; ++kk) kf[kk] = k1[kk];
.Lqk_go_2:
	v_mfma_f32_16x16x32_fp8_fp8 v[88:91], v[124:125], v[34:35], 0
	v_mfma_f32_16x16x32_fp8_fp8 v[88:91], v[126:127], v[32:33], v[88:91]
	v_mfma_f32_16x16x32_fp8_fp8 v[88:91], v[128:129], v[38:39], v[88:91]
	v_mfma_f32_16x16x32_fp8_fp8 v[88:91], v[130:131], v[36:37], v[88:91]
	v_mfma_f32_16x16x32_fp8_fp8 v[88:91], v[132:133], v[42:43], v[88:91]
	v_mfma_f32_16x16x32_fp8_fp8 v[88:91], v[134:135], v[40:41], v[88:91]
	v_mfma_f32_16x16x32_fp8_fp8 v[88:91], v[136:137], v[46:47], v[88:91]
	v_mfma_f32_16x16x32_fp8_fp8 v[88:91], v[138:139], v[44:45], v[88:91]
	s_and_saveexec_b64 s[12:13], s[8:9]
	s_waitcnt lgkmcnt(0)
	v_add_u32_e32 v165, v52, v25
	v_add_u32_e32 v166, v53, v25
	v_add_u32_e32 v167, v54, v25
	v_add_u32_e32 v168, v55, v25
	ds_read_b32 v165, v165
	ds_read_b32 v166, v166
	ds_read_b32 v167, v167
	ds_read_b32 v168, v168
	s_waitcnt lgkmcnt(3)
	v_fma_mixlo_f16 v165, v88, s3, v165
	s_waitcnt lgkmcnt(2)
	v_fma_mixlo_f16 v166, v89, s3, v166
	s_waitcnt lgkmcnt(1)
	v_fma_mixlo_f16 v167, v90, s3, v167
	s_waitcnt lgkmcnt(0)
	v_fma_mixlo_f16 v168, v91, s3, v168
	ds_write_b16 v143, v165 offset:512
	ds_write_b16 v143, v166 offset:528
	ds_write_b16 v143, v167 offset:544
	ds_write_b16 v143, v168 offset:560
	s_mov_b64 exec, s[12:13]
	s_cmp_le_i32 s16, 3
	s_cbranch_scc1 .Lqk_done
	ds_read_b128 v[52:55], v29 offset:192
	s_cmp_gt_i32 s16, 5
	s_cbranch_scc0 .Lqk_ni_3
	v_add_lshl_u32 v112, s48, v112, 8
	v_add_u32_e32 v112, v144, v112
	global_load_dwordx4 v[124:127], v112, s[84:85]
	global_load_dwordx4 v[128:131], v112, s[84:85] offset:64
	global_load_dwordx4 v[132:135], v112, s[84:85] offset:128
	global_load_dwordx4 v[136:139], v112, s[84:85] offset:192
	s_waitcnt vmcnt(8)
	s_branch .Lqk_go_3

; __device__ __forceinline__ void dsa_unit(int wv, const Args& A, LAS unsigned char* lds, int s, int qt) {
;     ...
;         for (int kt = 0; kt < nt; ++kt) {
;             long k1[8];
;             DSA_LOADT(k1, kt + 1);
;             f32x4 a = {0.f, 0.f, 0.f, 0.f};
; #pragma unroll
;             for (int kk = 0; kk < 8; ++kk) a = __builtin_amdgcn_mfma_f32_16x16x32_fp8_fp8(kf[kk], qf[kk], a, 0, 0, 0);
;             if (fr < 8) {
; #pragma unroll
;                 for (int r = 0; r < 4; ++r) { const int e2 = kt * 16 + fq * 4 + r; const int key2 = lst[e2];
;                     Pw[e2 * 8 + fr] = (h16)(a[r] * 0.0625f + relb[rel_bucket(key2 - qpos) * 8 + fr]); } }
; #pragma unroll
;             for (int kk = 0; kk < 8; ++kk) kf[kk] = k1[kk];
.Lqk_go_3:
	v_mfma_f32_16x16x32_fp8_fp8 v[88:91], v[56:57], v[34:35], 0
	v_mfma_f32_16x16x32_fp8_fp8 v[88:91], v[58:59], v[32:33], v[88:91]
	v_mfma_f32_16x16x32_fp8_fp8 v[88:91], v[60:61], v[38:39], v[88:91]
	v_mfma_f32_16x16x32_fp8_fp8 v[88:91], v[62:63], v[36:37], v[88:91]
	v_mfma_f32_16x16x32_fp8_fp8 v[88:91], v[64:65], v[42:43], v[88:91]
	v_mfma_f32_16x16x32_fp8_fp8 v[88:91], v[66:67], v[40:41], v[88:91]
	v_mfma_f32_16x16x32_fp8_fp8 v[88:91], v[68:69], v[46:47], v[88:91]
	v_mfma_f32_16x16x32_fp8_fp8 v[88:91], v[70:71], v[44:45], v[88:91]
	s_and_saveexec_b64 s[12:13], s[8:9]
	s_waitcnt lgkmcnt(0)
	v_add_u32_e32 v165, v52, v25
	v_add_u32_e32 v166, v53, v25
	v_add_u32_e32 v167, v54, v25
	v_add_u32_e32 v168, v55, v25
	ds_read_b32 v165, v165
	ds_read_b32 v166, v166
	ds_read_b32 v167, v167
	ds_read_b32 v168, v168
	s_waitcnt lgkmcnt(3)
	v_fma_mixlo_f16 v165, v88, s3, v165
	s_waitcnt lgkmcnt(2)
	v_fma_mixlo_f16 v166, v89, s3, v166
	s_waitcnt lgkmcnt(1)
	v_fma_mixlo_f16 v167, v90, s3, v167
	s_waitcnt lgkmcnt(0)
	v_fma_mixlo_f16 v168, v91, s3, v168
	ds_write_b16 v143, v165 offset:768
	ds_write_b16 v143, v166 offset:784
	ds_write_b16 v143, v167 offset:800
	ds_write_b16 v143, v168 offset:816
	s_mov_b64 exec, s[12:13]
	s_cmp_le_i32 s16, 4
	s_cbranch_scc1 .Lqk_done
	ds_read_b128 v[52:55], v29 offset:256
	s_cmp_gt_i32 s16, 6
	s_cbranch_scc0 .Lqk_ni_4
	v_add_lshl_u32 v113, s48, v113, 8
	v_add_u32_e32 v113, v144, v113
	global_load_dwordx4 v[56:59], v113, s[84:85]
	global_load_dwordx4 v[60:63], v113, s[84:85] offset:64
	global_load_dwordx4 v[64:67], v113, s[84:85] offset:128
	global_load_dwordx4 v[68:71], v113, s[84:85] offset:192
	s_waitcnt vmcnt(8)
	s_branch .Lqk_go_4

; __device__ __forceinline__ void dsa_unit(int wv, const Args& A, LAS unsigned char* lds, int s, int qt) {
;     ...
;         for (int kt = 0; kt < nt; ++kt) {
;             long k1[8];
;             DSA_LOADT(k1, kt + 1);
;             f32x4 a = {0.f, 0.f, 0.f, 0.f};
; #pragma unroll
;             for (int kk = 0; kk < 8; ++kk) a = __builtin_amdgcn_mfma_f32_16x16x32_fp8_fp8(kf[kk], qf[kk], a, 0, 0, 0);
;             if (fr < 8) {
; #pragma unroll
;                 for (int r = 0; r < 4; ++r) { const int e2 = kt * 16 + fq * 4 + r; const int key2 = lst[e2];
;                     Pw[e2 * 8 + fr] = (h16)(a[r] * 0.0625f + relb[rel_bucket(key2 - qpos) * 8 + fr]); } }
; #pragma unroll
;             for (int kk = 0; kk < 8; ++kk) kf[kk] = k1[kk];
.Lqk_go_4:
	v_mfma_f32_16x16x32_fp8_fp8 v[88:91], v[72:73], v[34:35], 0
	v_mfma_f32_16x16x32_fp8_fp8 v[88:91], v[74:75], v[32:33], v[88:91]
	v_mfma_f32_16x16x32_fp8_fp8 v[88:91], v[76:77], v[38:39], v[88:91]
	v_mfma_f32_16x16x32_fp8_fp8 v[88:91], v[78:79], v[36:37], v[88:91]
	v_mfma_f32_16x16x32_fp8_fp8 v[88:91], v[80:81], v[42:43], v[88:91]
	v_mfma_f32_16x16x32_fp8_fp8 v[88:91], v[82:83], v[40:41], v[88:91]
	v_mfma_f32_16x16x32_fp8_fp8 v[88:91], v[84:85], v[46:47], v[88:91]
	v_mfma_f32_16x16x32_fp8_fp8 v[88:91], v[86:87], v[44:45], v[88:91]
	s_and_saveexec_b64 s[12:13], s[8:9]
	s_waitcnt lgkmcnt(0)
	v_add_u32_e32 v165, v52, v25
	v_add_u32_e32 v166, v53, v25
	v_add_u32_e32 v167, v54, v25
	v_add_u32_e32 v168, v55, v25
	ds_read_b32 v165, v165
	ds_read_b32 v166, v166
	ds_read_b32 v167, v167
	ds_read_b32 v168, v168
	s_waitcnt lgkmcnt(3)
	v_fma_mixlo_f16 v165, v88, s3, v165
	s_waitcnt lgkmcnt(2)
	v_fma_mixlo_f16 v166, v89, s3, v166
	s_waitcnt lgkmcnt(1)
	v_fma_mixlo_f16 v167, v90, s3, v167
	s_waitcnt lgkmcnt(0)
	v_fma_mixlo_f16 v168, v91, s3, v168
	ds_write_b16 v143, v165 offset:1024
	ds_write_b16 v143, v166 offset:1040
	ds_write_b16 v143, v167 offset:1056
	ds_write_b16 v143, v168 offset:1072
	s_mov_b64 exec, s[12:13]
	s_cmp_le_i32 s16, 5
	s_cbranch_scc1 .Lqk_done
	ds_read_b128 v[52:55], v29 offset:320
	s_cmp_gt_i32 s16, 7
	s_cbranch_scc0 .Lqk_ni_5
	v_add_lshl_u32 v114, s48, v114, 8
	v_add_u32_e32 v114, v144, v114
	global_load_dwordx4 v[72:75], v114, s[84:85]
	global_load_dwordx4 v[76:79], v114, s[84:85] offset:64
	global_load_dwordx4 v[80:83], v114, s[84:85] offset:128
	global_load_dwordx4 v[84:87], v114, s[84:85] offset:192
	s_waitcnt vmcnt(8)
	s_branch .Lqk_go_5

; __device__ __forceinline__ void dsa_unit(int wv, const Args& A, LAS unsigned char* lds, int s, int qt) {
;     ...
;         for (int kt = 0; kt < nt; ++kt) {
;             long k1[8];
;             DSA_LOADT(k1, kt + 1);
;             f32x4 a = {0.f, 0.f, 0.f, 0.f};
; #pragma unroll
;             for (int kk = 0; kk < 8; ++kk) a = __builtin_amdgcn_mfma_f32_16x16x32_fp8_fp8(kf[kk], qf[kk], a, 0, 0, 0);
;             if (fr < 8) {
; #pragma unroll
;                 for (int r = 0; r < 4; ++r) { const int e2 = kt * 16 + fq * 4 + r; const int key2 = lst[e2];
;                     Pw[e2 * 8 + fr] = (h16)(a[r] * 0.0625f + relb[rel_bucket(key2 - qpos) * 8 + fr]); } }
; #pragma unroll
;             for (int kk = 0; kk < 8; ++kk) kf[kk] = k1[kk];
.Lqk_go_5:
	v_mfma_f32_16x16x32_fp8_fp8 v[88:91], v[124:125], v[34:35], 0
	v_mfma_f32_16x16x32_fp8_fp8 v[88:91], v[126:127], v[32:33], v[88:91]
	v_mfma_f32_16x16x32_fp8_fp8 v[88:91], v[128:129], v[38:39], v[88:91]
	v_mfma_f32_16x16x32_fp8_fp8 v[88:91], v[130:131], v[36:37], v[88:91]
	v_mfma_f32_16x16x32_fp8_fp8 v[88:91], v[132:133], v[42:43], v[88:91]
	v_mfma_f32_16x16x32_fp8_fp8 v[88:91], v[134:135], v[40:41], v[88:91]
	v_mfma_f32_16x16x32_fp8_fp8 v[88:91], v[136:137], v[46:47], v[88:91]
	v_mfma_f32_16x16x32_fp8_fp8 v[88:91], v[138:139], v[44:45], v[88:91]
	s_and_saveexec_b64 s[12:13], s[8:9]
	s_waitcnt lgkmcnt(0)
	v_add_u32_e32 v165, v52, v25
	v_add_u32_e32 v166, v53, v25
	v_add_u32_e32 v167, v54, v25
	v_add_u32_e32 v168, v55, v25
	ds_read_b32 v165, v165
	ds_read_b32 v166, v166
	ds_read_b32 v167, v167
	ds_read_b32 v168, v168
	s_waitcnt lgkmcnt(3)
	v_fma_mixlo_f16 v165, v88, s3, v165
	s_waitcnt lgkmcnt(2)
	v_fma_mixlo_f16 v166, v89, s3, v166
	s_waitcnt lgkmcnt(1)
	v_fma_mixlo_f16 v167, v90, s3, v167
	s_waitcnt lgkmcnt(0)
	v_fma_mixlo_f16 v168, v91, s3, v168
	ds_write_b16 v143, v165 offset:1280
	ds_write_b16 v143, v166 offset:1296
	ds_write_b16 v143, v167 offset:1312
	ds_write_b16 v143, v168 offset:1328
	s_mov_b64 exec, s[12:13]
	s_cmp_le_i32 s16, 6
	s_cbranch_scc1 .Lqk_done
	ds_read_b128 v[52:55], v29 offset:384
	s_cmp_gt_i32 s16, 8
	s_cbranch_scc0 .Lqk_ni_6
	v_add_lshl_u32 v115, s48, v115, 8
	v_add_u32_e32 v115, v144, v115
	global_load_dwordx4 v[124:127], v115, s[84:85]
	global_load_dwordx4 v[128:131], v115, s[84:85] offset:64
	global_load_dwordx4 v[132:135], v115, s[84:85] offset:128
	global_load_dwordx4 v[136:139], v115, s[84:85] offset:192
	s_waitcnt vmcnt(8)
	s_branch .Lqk_go_6

; __device__ __forceinline__ void dsa_unit(int wv, const Args& A, LAS unsigned char* lds, int s, int qt) {
;     ...
;         for (int kt = 0; kt < nt; ++kt) {
;             long k1[8];
;             DSA_LOADT(k1, kt + 1);
;             f32x4 a = {0.f, 0.f, 0.f, 0.f};
; #pragma unroll
;             for (int kk = 0; kk < 8; ++kk) a = __builtin_amdgcn_mfma_f32_16x16x32_fp8_fp8(kf[kk], qf[kk], a, 0, 0, 0);
;             if (fr < 8) {
; #pragma unroll
;                 for (int r = 0; r < 4; ++r) { const int e2 = kt * 16 + fq * 4 + r; const int key2 = lst[e2];
;                     Pw[e2 * 8 + fr] = (h16)(a[r] * 0.0625f + relb[rel_bucket(key2 - qpos) * 8 + fr]); } }
; #pragma unroll
;             for (int kk = 0; kk < 8; ++kk) kf[kk] = k1[kk];
.Lqk_go_6:
	v_mfma_f32_16x16x32_fp8_fp8 v[88:91], v[56:57], v[34:35], 0
	v_mfma_f32_16x16x32_fp8_fp8 v[88:91], v[58:59], v[32:33], v[88:91]
	v_mfma_f32_16x16x32_fp8_fp8 v[88:91], v[60:61], v[38:39], v[88:91]
	v_mfma_f32_16x16x32_fp8_fp8 v[88:91], v[62:63], v[36:37], v[88:91]
	v_mfma_f32_16x16x32_fp8_fp8 v[88:91], v[64:65], v[42:43], v[88:91]
	v_mfma_f32_16x16x32_fp8_fp8 v[88:91], v[66:67], v[40:41], v[88:91]
	v_mfma_f32_16x16x32_fp8_fp8 v[88:91], v[68:69], v[46:47], v[88:91]
	v_mfma_f32_16x16x32_fp8_fp8 v[88:91], v[70:71], v[44:45], v[88:91]
	s_and_saveexec_b64 s[12:13], s[8:9]
	s_waitcnt lgkmcnt(0)
	v_add_u32_e32 v165, v52, v25
	v_add_u32_e32 v166, v53, v25
	v_add_u32_e32 v167, v54, v25
	v_add_u32_e32 v168, v55, v25
	ds_read_b32 v165, v165
	ds_read_b32 v166, v166
	ds_read_b32 v167, v167
	ds_read_b32 v168, v168
	s_waitcnt lgkmcnt(3)
	v_fma_mixlo_f16 v165, v88, s3, v165
	s_waitcnt lgkmcnt(2)
	v_fma_mixlo_f16 v166, v89, s3, v166
	s_waitcnt lgkmcnt(1)
	v_fma_mixlo_f16 v167, v90, s3, v167
	s_waitcnt lgkmcnt(0)
	v_fma_mixlo_f16 v168, v91, s3, v168
	ds_write_b16 v143, v165 offset:1536
	ds_write_b16 v143, v166 offset:1552
	ds_write_b16 v143, v167 offset:1568
	ds_write_b16 v143, v168 offset:1584
	s_mov_b64 exec, s[12:13]
	s_cmp_le_i32 s16, 7
	s_cbranch_scc1 .Lqk_done
	ds_read_b128 v[52:55], v29 offset:448
	s_cmp_gt_i32 s16, 9
	s_cbranch_scc0 .Lqk_ni_7
	v_add_lshl_u32 v116, s48, v116, 8
	v_add_u32_e32 v116, v144, v116
	global_load_dwordx4 v[56:59], v116, s[84:85]
	global_load_dwordx4 v[60:63], v116, s[84:85] offset:64
	global_load_dwordx4 v[64:67], v116, s[84:85] offset:128
	global_load_dwordx4 v[68:71], v116, s[84:85] offset:192
	s_waitcnt vmcnt(8)
	s_branch .Lqk_go_7

; __device__ __forceinline__ void dsa_unit(int wv, const Args& A, LAS unsigned char* lds, int s, int qt) {
;     ...
;         for (int kt = 0; kt < nt; ++kt) {
;             long k1[8];
;             DSA_LOADT(k1, kt + 1);
;             f32x4 a = {0.f, 0.f, 0.f, 0.f};
; #pragma unroll
;             for (int kk = 0; kk < 8; ++kk) a = __builtin_amdgcn_mfma_f32_16x16x32_fp8_fp8(kf[kk], qf[kk], a, 0, 0, 0);
;             if (fr < 8) {
; #pragma unroll
;                 for (int r = 0; r < 4; ++r) { const int e2 = kt * 16 + fq * 4 + r; const int key2 = lst[e2];
;                     Pw[e2 * 8 + fr] = (h16)(a[r] * 0.0625f + relb[rel_bucket(key2 - qpos) * 8 + fr]); } }
; #pragma unroll
;             for (int kk = 0; kk < 8; ++kk) kf[kk] = k1[kk];
.Lqk_go_7:
	v_mfma_f32_16x16x32_fp8_fp8 v[88:91], v[72:73], v[34:35], 0
	v_mfma_f32_16x16x32_fp8_fp8 v[88:91], v[74:75], v[32:33], v[88:91]
	v_mfma_f32_16x16x32_fp8_fp8 v[88:91], v[76:77], v[38:39], v[88:91]
	v_mfma_f32_16x16x32_fp8_fp8 v[88:91], v[78:79], v[36:37], v[88:91]
	v_mfma_f32_16x16x32_fp8_fp8 v[88:91], v[80:81], v[42:43], v[88:91]
	v_mfma_f32_16x16x32_fp8_fp8 v[88:91], v[82:83], v[40:41], v[88:91]
	v_mfma_f32_16x16x32_fp8_fp8 v[88:91], v[84:85], v[46:47], v[88:91]
	v_mfma_f32_16x16x32_fp8_fp8 v[88:91], v[86:87], v[44:45], v[88:91]
	s_and_saveexec_b64 s[12:13], s[8:9]
	s_waitcnt lgkmcnt(0)
	v_add_u32_e32 v165, v52, v25
	v_add_u32_e32 v166, v53, v25
	v_add_u32_e32 v167, v54, v25
	v_add_u32_e32 v168, v55, v25
	ds_read_b32 v165, v165
	ds_read_b32 v166, v166
	ds_read_b32 v167, v167
	ds_read_b32 v168, v168
	s_waitcnt lgkmcnt(3)
	v_fma_mixlo_f16 v165, v88, s3, v165
	s_waitcnt lgkmcnt(2)
	v_fma_mixlo_f16 v166, v89, s3, v166
	s_waitcnt lgkmcnt(1)
	v_fma_mixlo_f16 v167, v90, s3, v167
	s_waitcnt lgkmcnt(0)
	v_fma_mixlo_f16 v168, v91, s3, v168
	ds_write_b16 v143, v165 offset:1792
	ds_write_b16 v143, v166 offset:1808
	ds_write_b16 v143, v167 offset:1824
	ds_write_b16 v143, v168 offset:1840
	s_mov_b64 exec, s[12:13]
	s_cmp_le_i32 s16, 8
	s_cbranch_scc1 .Lqk_done
	ds_read_b128 v[52:55], v29 offset:512
	s_cmp_gt_i32 s16, 10
	s_cbranch_scc0 .Lqk_ni_8
	v_add_lshl_u32 v117, s48, v117, 8
	v_add_u32_e32 v117, v144, v117
	global_load_dwordx4 v[72:75], v117, s[84:85]
	global_load_dwordx4 v[76:79], v117, s[84:85] offset:64
	global_load_dwordx4 v[80:83], v117, s[84:85] offset:128
	global_load_dwordx4 v[84:87], v117, s[84:85] offset:192
	s_waitcnt vmcnt(8)
	s_branch .Lqk_go_8

; __device__ __forceinline__ void dsa_unit(int wv, const Args& A, LAS unsigned char* lds, int s, int qt) {
;     ...
;         for (int kt = 0; kt < nt; ++kt) {
;             long k1[8];
;             DSA_LOADT(k1, kt + 1);
;             f32x4 a = {0.f, 0.f, 0.f, 0.f};
; #pragma unroll
;             for (int kk = 0; kk < 8; ++kk) a = __builtin_amdgcn_mfma_f32_16x16x32_fp8_fp8(kf[kk], qf[kk], a, 0, 0, 0);
;             if (fr < 8) {
; #pragma unroll
;                 for (int r = 0; r < 4; ++r) { const int e2 = kt * 16 + fq * 4 + r; const int key2 = lst[e2];
;                     Pw[e2 * 8 + fr] = (h16)(a[r] * 0.0625f + relb[rel_bucket(key2 - qpos) * 8 + fr]); } }
; #pragma unroll
;             for (int kk = 0; kk < 8; ++kk) kf[kk] = k1[kk];
.Lqk_go_8:
	v_mfma_f32_16x16x32_fp8_fp8 v[88:91], v[124:125], v[34:35], 0
	v_mfma_f32_16x16x32_fp8_fp8 v[88:91], v[126:127], v[32:33], v[88:91]
	v_mfma_f32_16x16x32_fp8_fp8 v[88:91], v[128:129], v[38:39], v[88:91]
	v_mfma_f32_16x16x32_fp8_fp8 v[88:91], v[130:131], v[36:37], v[88:91]
	v_mfma_f32_16x16x32_fp8_fp8 v[88:91], v[132:133], v[42:43], v[88:91]
	v_mfma_f32_16x16x32_fp8_fp8 v[88:91], v[134:135], v[40:41], v[88:91]
	v_mfma_f32_16x16x32_fp8_fp8 v[88:91], v[136:137], v[46:47], v[88:91]
	v_mfma_f32_16x16x32_fp8_fp8 v[88:91], v[138:139], v[44:45], v[88:91]
	s_and_saveexec_b64 s[12:13], s[8:9]
	s_waitcnt lgkmcnt(0)
	v_add_u32_e32 v165, v52, v25
	v_add_u32_e32 v166, v53, v25
	v_add_u32_e32 v167, v54, v25
	v_add_u32_e32 v168, v55, v25
	ds_read_b32 v165, v165
	ds_read_b32 v166, v166
	ds_read_b32 v167, v167
	ds_read_b32 v168, v168
	s_waitcnt lgkmcnt(3)
	v_fma_mixlo_f16 v165, v88, s3, v165
	s_waitcnt lgkmcnt(2)
	v_fma_mixlo_f16 v166, v89, s3, v166
	s_waitcnt lgkmcnt(1)
	v_fma_mixlo_f16 v167, v90, s3, v167
	s_waitcnt lgkmcnt(0)
	v_fma_mixlo_f16 v168, v91, s3, v168
	ds_write_b16 v143, v165 offset:2048
	ds_write_b16 v143, v166 offset:2064
	ds_write_b16 v143, v167 offset:2080
	ds_write_b16 v143, v168 offset:2096
	s_mov_b64 exec, s[12:13]
	s_cmp_le_i32 s16, 9
	s_cbranch_scc1 .Lqk_done
	ds_read_b128 v[52:55], v29 offset:576
	s_cmp_gt_i32 s16, 11
	s_cbranch_scc0 .Lqk_ni_9
	v_add_lshl_u32 v118, s48, v118, 8
	v_add_u32_e32 v118, v144, v118
	global_load_dwordx4 v[124:127], v118, s[84:85]
	global_load_dwordx4 v[128:131], v118, s[84:85] offset:64
	global_load_dwordx4 v[132:135], v118, s[84:85] offset:128
	global_load_dwordx4 v[136:139], v118, s[84:85] offset:192
	s_waitcnt vmcnt(8)
	s_branch .Lqk_go_9

; __device__ __forceinline__ void dsa_unit(int wv, const Args& A, LAS unsigned char* lds, int s, int qt) {
;     ...
;         for (int kt = 0; kt < nt; ++kt) {
;             long k1[8];
;             DSA_LOADT(k1, kt + 1);
;             f32x4 a = {0.f, 0.f, 0.f, 0.f};
; #pragma unroll
;             for (int kk = 0; kk < 8; ++kk) a = __builtin_amdgcn_mfma_f32_16x16x32_fp8_fp8(kf[kk], qf[kk], a, 0, 0, 0);
;             if (fr < 8) {
; #pragma unroll
;                 for (int r = 0; r < 4; ++r) { const int e2 = kt * 16 + fq * 4 + r; const int key2 = lst[e2];
;                     Pw[e2 * 8 + fr] = (h16)(a[r] * 0.0625f + relb[rel_bucket(key2 - qpos) * 8 + fr]); } }
; #pragma unroll
;             for (int kk = 0; kk < 8; ++kk) kf[kk] = k1[kk];
.Lqk_go_9:
	v_mfma_f32_16x16x32_fp8_fp8 v[88:91], v[56:57], v[34:35], 0
	v_mfma_f32_16x16x32_fp8_fp8 v[88:91], v[58:59], v[32:33], v[88:91]
	v_mfma_f32_16x16x32_fp8_fp8 v[88:91], v[60:61], v[38:39], v[88:91]
	v_mfma_f32_16x16x32_fp8_fp8 v[88:91], v[62:63], v[36:37], v[88:91]
	v_mfma_f32_16x16x32_fp8_fp8 v[88:91], v[64:65], v[42:43], v[88:91]
	v_mfma_f32_16x16x32_fp8_fp8 v[88:91], v[66:67], v[40:41], v[88:91]
	v_mfma_f32_16x16x32_fp8_fp8 v[88:91], v[68:69], v[46:47], v[88:91]
	v_mfma_f32_16x16x32_fp8_fp8 v[88:91], v[70:71], v[44:45], v[88:91]
	s_and_saveexec_b64 s[12:13], s[8:9]
	s_waitcnt lgkmcnt(0)
	v_add_u32_e32 v165, v52, v25
	v_add_u32_e32 v166, v53, v25
	v_add_u32_e32 v167, v54, v25
	v_add_u32_e32 v168, v55, v25
	ds_read_b32 v165, v165
	ds_read_b32 v166, v166
	ds_read_b32 v167, v167
	ds_read_b32 v168, v168
	s_waitcnt lgkmcnt(3)
	v_fma_mixlo_f16 v165, v88, s3, v165
	s_waitcnt lgkmcnt(2)
	v_fma_mixlo_f16 v166, v89, s3, v166
	s_waitcnt lgkmcnt(1)
	v_fma_mixlo_f16 v167, v90, s3, v167
	s_waitcnt lgkmcnt(0)
	v_fma_mixlo_f16 v168, v91, s3, v168
	ds_write_b16 v143, v165 offset:2304
	ds_write_b16 v143, v166 offset:2320
	ds_write_b16 v143, v167 offset:2336
	ds_write_b16 v143, v168 offset:2352
	s_mov_b64 exec, s[12:13]
	s_cmp_le_i32 s16, 10
	s_cbranch_scc1 .Lqk_done
	ds_read_b128 v[52:55], v29 offset:640
	s_cmp_gt_i32 s16, 12
	s_cbranch_scc0 .Lqk_ni_10
	v_add_lshl_u32 v119, s48, v119, 8
	v_add_u32_e32 v119, v144, v119
	global_load_dwordx4 v[56:59], v119, s[84:85]
	global_load_dwordx4 v[60:63], v119, s[84:85] offset:64
	global_load_dwordx4 v[64:67], v119, s[84:85] offset:128
	global_load_dwordx4 v[68:71], v119, s[84:85] offset:192
	s_waitcnt vmcnt(8)
	s_branch .Lqk_go_10

; __device__ __forceinline__ void dsa_unit(int wv, const Args& A, LAS unsigned char* lds, int s, int qt) {
;     ...
;         for (int kt = 0; kt < nt; ++kt) {
;             long k1[8];
;             DSA_LOADT(k1, kt + 1);
;             f32x4 a = {0.f, 0.f, 0.f, 0.f};
; #pragma unroll
;             for (int kk = 0; kk < 8; ++kk) a = __builtin_amdgcn_mfma_f32_16x16x32_fp8_fp8(kf[kk], qf[kk], a, 0, 0, 0);
;             if (fr < 8) {
; #pragma unroll
;                 for (int r = 0; r < 4; ++r) { const int e2 = kt * 16 + fq * 4 + r; const int key2 = lst[e2];
;                     Pw[e2 * 8 + fr] = (h16)(a[r] * 0.0625f + relb[rel_bucket(key2 - qpos) * 8 + fr]); } }
; #pragma unroll
;             for (int kk = 0; kk < 8; ++kk) kf[kk] = k1[kk];
.Lqk_go_10:
	v_mfma_f32_16x16x32_fp8_fp8 v[88:91], v[72:73], v[34:35], 0
	v_mfma_f32_16x16x32_fp8_fp8 v[88:91], v[74:75], v[32:33], v[88:91]
	v_mfma_f32_16x16x32_fp8_fp8 v[88:91], v[76:77], v[38:39], v[88:91]
	v_mfma_f32_16x16x32_fp8_fp8 v[88:91], v[78:79], v[36:37], v[88:91]
	v_mfma_f32_16x16x32_fp8_fp8 v[88:91], v[80:81], v[42:43], v[88:91]
	v_mfma_f32_16x16x32_fp8_fp8 v[88:91], v[82:83], v[40:41], v[88:91]
	v_mfma_f32_16x16x32_fp8_fp8 v[88:91], v[84:85], v[46:47], v[88:91]
	v_mfma_f32_16x16x32_fp8_fp8 v[88:91], v[86:87], v[44:45], v[88:91]
	s_and_saveexec_b64 s[12:13], s[8:9]
	s_waitcnt lgkmcnt(0)
	v_add_u32_e32 v165, v52, v25
	v_add_u32_e32 v166, v53, v25
	v_add_u32_e32 v167, v54, v25
	v_add_u32_e32 v168, v55, v25
	ds_read_b32 v165, v165
	ds_read_b32 v166, v166
	ds_read_b32 v167, v167
	ds_read_b32 v168, v168
	s_waitcnt lgkmcnt(3)
	v_fma_mixlo_f16 v165, v88, s3, v165
	s_waitcnt lgkmcnt(2)
	v_fma_mixlo_f16 v166, v89, s3, v166
	s_waitcnt lgkmcnt(1)
	v_fma_mixlo_f16 v167, v90, s3, v167
	s_waitcnt lgkmcnt(0)
	v_fma_mixlo_f16 v168, v91, s3, v168
	ds_write_b16 v143, v165 offset:2560
	ds_write_b16 v143, v166 offset:2576
	ds_write_b16 v143, v167 offset:2592
	ds_write_b16 v143, v168 offset:2608
	s_mov_b64 exec, s[12:13]
	s_cmp_le_i32 s16, 11
	s_cbranch_scc1 .Lqk_done
	ds_read_b128 v[52:55], v29 offset:704
	s_cmp_gt_i32 s16, 13
	s_cbranch_scc0 .Lqk_ni_11
	v_add_lshl_u32 v120, s48, v120, 8
	v_add_u32_e32 v120, v144, v120
	global_load_dwordx4 v[72:75], v120, s[84:85]
	global_load_dwordx4 v[76:79], v120, s[84:85] offset:64
	global_load_dwordx4 v[80:83], v120, s[84:85] offset:128
	global_load_dwordx4 v[84:87], v120, s[84:85] offset:192
	s_waitcnt vmcnt(8)
	s_branch .Lqk_go_11

; __device__ __forceinline__ void dsa_unit(int wv, const Args& A, LAS unsigned char* lds, int s, int qt) {
;     ...
;         for (int kt = 0; kt < nt; ++kt) {
;             long k1[8];
;             DSA_LOADT(k1, kt + 1);
;             f32x4 a = {0.f, 0.f, 0.f, 0.f};
; #pragma unroll
;             for (int kk = 0; kk < 8; ++kk) a = __builtin_amdgcn_mfma_f32_16x16x32_fp8_fp8(kf[kk], qf[kk], a, 0, 0, 0);
;             if (fr < 8) {
; #pragma unroll
;                 for (int r = 0; r < 4; ++r) { const int e2 = kt * 16 + fq * 4 + r; const int key2 = lst[e2];
;                     Pw[e2 * 8 + fr] = (h16)(a[r] * 0.0625f + relb[rel_bucket(key2 - qpos) * 8 + fr]); } }
; #pragma unroll
;             for (int kk = 0; kk < 8; ++kk) kf[kk] = k1[kk];
.Lqk_go_11:
	v_mfma_f32_16x16x32_fp8_fp8 v[88:91], v[124:125], v[34:35], 0
	v_mfma_f32_16x16x32_fp8_fp8 v[88:91], v[126:127], v[32:33], v[88:91]
	v_mfma_f32_16x16x32_fp8_fp8 v[88:91], v[128:129], v[38:39], v[88:91]
	v_mfma_f32_16x16x32_fp8_fp8 v[88:91], v[130:131], v[36:37], v[88:91]
	v_mfma_f32_16x16x32_fp8_fp8 v[88:91], v[132:133], v[42:43], v[88:91]
	v_mfma_f32_16x16x32_fp8_fp8 v[88:91], v[134:135], v[40:41], v[88:91]
	v_mfma_f32_16x16x32_fp8_fp8 v[88:91], v[136:137], v[46:47], v[88:91]
	v_mfma_f32_16x16x32_fp8_fp8 v[88:91], v[138:139], v[44:45], v[88:91]
	s_and_saveexec_b64 s[12:13], s[8:9]
	s_waitcnt lgkmcnt(0)
	v_add_u32_e32 v165, v52, v25
	v_add_u32_e32 v166, v53, v25
	v_add_u32_e32 v167, v54, v25
	v_add_u32_e32 v168, v55, v25
	ds_read_b32 v165, v165
	ds_read_b32 v166, v166
	ds_read_b32 v167, v167
	ds_read_b32 v168, v168
	s_waitcnt lgkmcnt(3)
	v_fma_mixlo_f16 v165, v88, s3, v165
	s_waitcnt lgkmcnt(2)
	v_fma_mixlo_f16 v166, v89, s3, v166
	s_waitcnt lgkmcnt(1)
	v_fma_mixlo_f16 v167, v90, s3, v167
	s_waitcnt lgkmcnt(0)
	v_fma_mixlo_f16 v168, v91, s3, v168
	ds_write_b16 v143, v165 offset:2816
	ds_write_b16 v143, v166 offset:2832
	ds_write_b16 v143, v167 offset:2848
	ds_write_b16 v143, v168 offset:2864
	s_mov_b64 exec, s[12:13]
	s_cmp_le_i32 s16, 12
	s_cbranch_scc1 .Lqk_done
	ds_read_b128 v[52:55], v29 offset:768
	s_cmp_gt_i32 s16, 14
	s_cbranch_scc0 .Lqk_ni_12
	v_add_lshl_u32 v121, s48, v121, 8
	v_add_u32_e32 v121, v144, v121
	global_load_dwordx4 v[124:127], v121, s[84:85]
	global_load_dwordx4 v[128:131], v121, s[84:85] offset:64
	global_load_dwordx4 v[132:135], v121, s[84:85] offset:128
	global_load_dwordx4 v[136:139], v121, s[84:85] offset:192
	s_waitcnt vmcnt(8)
	s_branch .Lqk_go_12

; __device__ __forceinline__ void dsa_unit(int wv, const Args& A, LAS unsigned char* lds, int s, int qt) {
;     ...
;         for (int kt = 0; kt < nt; ++kt) {
;             long k1[8];
;             DSA_LOADT(k1, kt + 1);
;             f32x4 a = {0.f, 0.f, 0.f, 0.f};
; #pragma unroll
;             for (int kk = 0; kk < 8; ++kk) a = __builtin_amdgcn_mfma_f32_16x16x32_fp8_fp8(kf[kk], qf[kk], a, 0, 0, 0);
;             if (fr < 8) {
; #pragma unroll
;                 for (int r = 0; r < 4; ++r) { const int e2 = kt * 16 + fq * 4 + r; const int key2 = lst[e2];
;                     Pw[e2 * 8 + fr] = (h16)(a[r] * 0.0625f + relb[rel_bucket(key2 - qpos) * 8 + fr]); } }
; #pragma unroll
;             for (int kk = 0; kk < 8; ++kk) kf[kk] = k1[kk];
.Lqk_go_12:
	v_mfma_f32_16x16x32_fp8_fp8 v[88:91], v[56:57], v[34:35], 0
	v_mfma_f32_16x16x32_fp8_fp8 v[88:91], v[58:59], v[32:33], v[88:91]
	v_mfma_f32_16x16x32_fp8_fp8 v[88:91], v[60:61], v[38:39], v[88:91]
	v_mfma_f32_16x16x32_fp8_fp8 v[88:91], v[62:63], v[36:37], v[88:91]
	v_mfma_f32_16x16x32_fp8_fp8 v[88:91], v[64:65], v[42:43], v[88:91]
	v_mfma_f32_16x16x32_fp8_fp8 v[88:91], v[66:67], v[40:41], v[88:91]
	v_mfma_f32_16x16x32_fp8_fp8 v[88:91], v[68:69], v[46:47], v[88:91]
	v_mfma_f32_16x16x32_fp8_fp8 v[88:91], v[70:71], v[44:45], v[88:91]
	s_and_saveexec_b64 s[12:13], s[8:9]
	s_waitcnt lgkmcnt(0)
	v_add_u32_e32 v165, v52, v25
	v_add_u32_e32 v166, v53, v25
	v_add_u32_e32 v167, v54, v25
	v_add_u32_e32 v168, v55, v25
	ds_read_b32 v165, v165
	ds_read_b32 v166, v166
	ds_read_b32 v167, v167
	ds_read_b32 v168, v168
	s_waitcnt lgkmcnt(3)
	v_fma_mixlo_f16 v165, v88, s3, v165
	s_waitcnt lgkmcnt(2)
	v_fma_mixlo_f16 v166, v89, s3, v166
	s_waitcnt lgkmcnt(1)
	v_fma_mixlo_f16 v167, v90, s3, v167
	s_waitcnt lgkmcnt(0)
	v_fma_mixlo_f16 v168, v91, s3, v168
	ds_write_b16 v143, v165 offset:3072
	ds_write_b16 v143, v166 offset:3088
	ds_write_b16 v143, v167 offset:3104
	ds_write_b16 v143, v168 offset:3120
	s_mov_b64 exec, s[12:13]
	s_cmp_le_i32 s16, 13
	s_cbranch_scc1 .Lqk_done
	ds_read_b128 v[52:55], v29 offset:832
	s_cmp_gt_i32 s16, 15
	s_cbranch_scc0 .Lqk_ni_13
	v_add_lshl_u32 v122, s48, v122, 8
	v_add_u32_e32 v122, v144, v122
	global_load_dwordx4 v[56:59], v122, s[84:85]
	global_load_dwordx4 v[60:63], v122, s[84:85] offset:64
	global_load_dwordx4 v[64:67], v122, s[84:85] offset:128
	global_load_dwordx4 v[68:71], v122, s[84:85] offset:192
	s_waitcnt vmcnt(8)
	s_branch .Lqk_go_13

; __device__ __forceinline__ void dsa_unit(int wv, const Args& A, LAS unsigned char* lds, int s, int qt) {
;     ...
;         for (int kt = 0; kt < nt; ++kt) {
;             long k1[8];
;             DSA_LOADT(k1, kt + 1);
;             f32x4 a = {0.f, 0.f, 0.f, 0.f};
; #pragma unroll
;             for (int kk = 0; kk < 8; ++kk) a = __builtin_amdgcn_mfma_f32_16x16x32_fp8_fp8(kf[kk], qf[kk], a, 0, 0, 0);
;             if (fr < 8) {
; #pragma unroll
;                 for (int r = 0; r < 4; ++r) { const int e2 = kt * 16 + fq * 4 + r; const int key2 = lst[e2];
;                     Pw[e2 * 8 + fr] = (h16)(a[r] * 0.0625f + relb[rel_bucket(key2 - qpos) * 8 + fr]); } }
; #pragma unroll
;             for (int kk = 0; kk < 8; ++kk) kf[kk] = k1[kk];
.Lqk_go_13:
	v_mfma_f32_16x16x32_fp8_fp8 v[88:91], v[72:73], v[34:35], 0
	v_mfma_f32_16x16x32_fp8_fp8 v[88:91], v[74:75], v[32:33], v[88:91]
	v_mfma_f32_16x16x32_fp8_fp8 v[88:91], v[76:77], v[38:39], v[88:91]
	v_mfma_f32_16x16x32_fp8_fp8 v[88:91], v[78:79], v[36:37], v[88:91]
	v_mfma_f32_16x16x32_fp8_fp8 v[88:91], v[80:81], v[42:43], v[88:91]
	v_mfma_f32_16x16x32_fp8_fp8 v[88:91], v[82:83], v[40:41], v[88:91]
	v_mfma_f32_16x16x32_fp8_fp8 v[88:91], v[84:85], v[46:47], v[88:91]
	v_mfma_f32_16x16x32_fp8_fp8 v[88:91], v[86:87], v[44:45], v[88:91]
	s_and_saveexec_b64 s[12:13], s[8:9]
	s_waitcnt lgkmcnt(0)
	v_add_u32_e32 v165, v52, v25
	v_add_u32_e32 v166, v53, v25
	v_add_u32_e32 v167, v54, v25
	v_add_u32_e32 v168, v55, v25
	ds_read_b32 v165, v165
	ds_read_b32 v166, v166
	ds_read_b32 v167, v167
	ds_read_b32 v168, v168
	s_waitcnt lgkmcnt(3)
	v_fma_mixlo_f16 v165, v88, s3, v165
	s_waitcnt lgkmcnt(2)
	v_fma_mixlo_f16 v166, v89, s3, v166
	s_waitcnt lgkmcnt(1)
	v_fma_mixlo_f16 v167, v90, s3, v167
	s_waitcnt lgkmcnt(0)
	v_fma_mixlo_f16 v168, v91, s3, v168
	ds_write_b16 v143, v165 offset:3328
	ds_write_b16 v143, v166 offset:3344
	ds_write_b16 v143, v167 offset:3360
	ds_write_b16 v143, v168 offset:3376
	s_mov_b64 exec, s[12:13]
	s_cmp_le_i32 s16, 14
	s_cbranch_scc1 .Lqk_done
	ds_read_b128 v[52:55], v29 offset:896
	s_cmp_gt_i32 s16, 15
	s_cbranch_scc0 .Lqk_nj_14
	s_waitcnt vmcnt(4)
	s_branch .Lqk_go_14

; __device__ __forceinline__ void dsa_unit(int wv, const Args& A, LAS unsigned char* lds, int s, int qt) {
;     ...
;         for (int kt = 0; kt < nt; ++kt) {
;             long k1[8];
;             DSA_LOADT(k1, kt + 1);
;             f32x4 a = {0.f, 0.f, 0.f, 0.f};
; #pragma unroll
;             for (int kk = 0; kk < 8; ++kk) a = __builtin_amdgcn_mfma_f32_16x16x32_fp8_fp8(kf[kk], qf[kk], a, 0, 0, 0);
;             if (fr < 8) {
; #pragma unroll
;                 for (int r = 0; r < 4; ++r) { const int e2 = kt * 16 + fq * 4 + r; const int key2 = lst[e2];
;                     Pw[e2 * 8 + fr] = (h16)(a[r] * 0.0625f + relb[rel_bucket(key2 - qpos) * 8 + fr]); } }
; #pragma unroll
;             for (int kk = 0; kk < 8; ++kk) kf[kk] = k1[kk];
.Lqk_go_14:
	v_mfma_f32_16x16x32_fp8_fp8 v[88:91], v[124:125], v[34:35], 0
	v_mfma_f32_16x16x32_fp8_fp8 v[88:91], v[126:127], v[32:33], v[88:91]
	v_mfma_f32_16x16x32_fp8_fp8 v[88:91], v[128:129], v[38:39], v[88:91]
	v_mfma_f32_16x16x32_fp8_fp8 v[88:91], v[130:131], v[36:37], v[88:91]
	v_mfma_f32_16x16x32_fp8_fp8 v[88:91], v[132:133], v[42:43], v[88:91]
	v_mfma_f32_16x16x32_fp8_fp8 v[88:91], v[134:135], v[40:41], v[88:91]
	v_mfma_f32_16x16x32_fp8_fp8 v[88:91], v[136:137], v[46:47], v[88:91]
	v_mfma_f32_16x16x32_fp8_fp8 v[88:91], v[138:139], v[44:45], v[88:91]
	s_and_saveexec_b64 s[12:13], s[8:9]
	s_waitcnt lgkmcnt(0)
	v_add_u32_e32 v165, v52, v25
	v_add_u32_e32 v166, v53, v25
	v_add_u32_e32 v167, v54, v25
	v_add_u32_e32 v168, v55, v25
	ds_read_b32 v165, v165
	ds_read_b32 v166, v166
	ds_read_b32 v167, v167
	ds_read_b32 v168, v168
	s_waitcnt lgkmcnt(3)
	v_fma_mixlo_f16 v165, v88, s3, v165
	s_waitcnt lgkmcnt(2)
	v_fma_mixlo_f16 v166, v89, s3, v166
	s_waitcnt lgkmcnt(1)
	v_fma_mixlo_f16 v167, v90, s3, v167
	s_waitcnt lgkmcnt(0)
	v_fma_mixlo_f16 v168, v91, s3, v168
	ds_write_b16 v143, v165 offset:3584
	ds_write_b16 v143, v166 offset:3600
	ds_write_b16 v143, v167 offset:3616
	ds_write_b16 v143, v168 offset:3632
	s_mov_b64 exec, s[12:13]
	s_cmp_le_i32 s16, 15
	s_cbranch_scc1 .Lqk_done
	ds_read_b128 v[52:55], v29 offset:960
	s_waitcnt vmcnt(0)
.Lqk_go_15:
	v_mfma_f32_16x16x32_fp8_fp8 v[88:91], v[56:57], v[34:35], 0
	v_mfma_f32_16x16x32_fp8_fp8 v[88:91], v[58:59], v[32:33], v[88:91]
	v_mfma_f32_16x16x32_fp8_fp8 v[88:91], v[60:61], v[38:39], v[88:91]
	v_mfma_f32_16x16x32_fp8_fp8 v[88:91], v[62:63], v[36:37], v[88:91]
	v_mfma_f32_16x16x32_fp8_fp8 v[88:91], v[64:65], v[42:43], v[88:91]
	v_mfma_f32_16x16x32_fp8_fp8 v[88:91], v[66:67], v[40:41], v[88:91]
	v_mfma_f32_16x16x32_fp8_fp8 v[88:91], v[68:69], v[46:47], v[88:91]
	v_mfma_f32_16x16x32_fp8_fp8 v[88:91], v[70:71], v[44:45], v[88:91]
	s_and_saveexec_b64 s[12:13], s[8:9]
	s_waitcnt lgkmcnt(0)
	v_add_u32_e32 v165, v52, v25
	v_add_u32_e32 v166, v53, v25
	v_add_u32_e32 v167, v54, v25
	v_add_u32_e32 v168, v55, v25
	ds_read_b32 v165, v165
	ds_read_b32 v166, v166
	ds_read_b32 v167, v167
	ds_read_b32 v168, v168
	s_waitcnt lgkmcnt(3)
	v_fma_mixlo_f16 v165, v88, s3, v165
	s_waitcnt lgkmcnt(2)
	v_fma_mixlo_f16 v166, v89, s3, v166
	s_waitcnt lgkmcnt(1)
	v_fma_mixlo_f16 v167, v90, s3, v167
	s_waitcnt lgkmcnt(0)
	v_fma_mixlo_f16 v168, v91, s3, v168
	ds_write_b16 v143, v165 offset:3840
	ds_write_b16 v143, v166 offset:3856
	ds_write_b16 v143, v167 offset:3872
	ds_write_b16 v143, v168 offset:3888
	s_mov_b64 exec, s[12:13]
